# adds YRES epilogue: permlane swaps instead of ds_bpermute, gain+X row loads hoisted/pipelined 3 rows ahead
# speedup vs baseline: 1.0025x; 1.0025x over previous
.LBB0_337:
	s_and_b64 vcc, exec, s[0:1]
	s_cbranch_vccz .LBB0_420
	s_lshl_b32 s100, s55, 8
	v_add_u32_e32 v218, s100, v147
	v_ashrrev_i32_e32 v219, 31, v218
	v_lshlrev_b64 v[218:219], 11, v[218:219]
	v_lshl_or_b32 v172, s10, 8, v156
	v_ashrrev_i32_e32 v173, 31, v172
	v_lshl_add_u64 v[218:219], s[4:5], 0, v[218:219]
	v_lshl_add_u64 v[218:219], v[172:173], 1, v[218:219]
	v_lshl_add_u64 v[172:173], v[172:173], 2, s[72:73]
	global_load_dwordx4 v[186:189], v[172:173], off
	global_load_dwordx4 v[190:193], v[172:173], off offset:16
	global_load_dwordx4 v[194:197], v[172:173], off offset:512
	global_load_dwordx4 v[198:201], v[172:173], off offset:528
	global_load_dwordx4 v[202:205], v[218:219], off
	global_load_dwordx4 v[206:209], v[218:219], off offset:256
	s_mov_b32 s100, 0x8000
	s_mov_b32 s101, 0
	v_lshl_add_u64 v[172:173], v[218:219], 0, s[100:101]
	global_load_dwordx4 v[210:213], v[172:173], off
	global_load_dwordx4 v[214:217], v[172:173], off offset:256
	v_lshl_add_u64 v[172:173], v[172:173], 0, s[100:101]
	global_load_dwordx4 v[232:235], v[172:173], off
	global_load_dwordx4 v[246:249], v[172:173], off offset:256
	v_pk_mul_f32 v[128:129], v[126:127], v[126:127]
	v_pk_mul_f32 v[130:131], v[124:125], v[124:125]
	v_pk_fma_f32 v[128:129], v[122:123], v[122:123], v[128:129]
	v_pk_fma_f32 v[130:131], v[120:121], v[120:121], v[130:131]
	v_pk_fma_f32 v[128:129], v[118:119], v[118:119], v[128:129]
	v_pk_fma_f32 v[130:131], v[116:117], v[116:117], v[130:131]
	v_pk_fma_f32 v[128:129], v[114:115], v[114:115], v[128:129]
	v_pk_fma_f32 v[130:131], v[112:113], v[112:113], v[130:131]
	v_add_f32_e32 v128, v128, v129
	v_add_f32_e32 v130, v130, v131
	v_add_f32_e32 v128, v130, v128
	v_mov_b32_e32 v129, v128
	s_nop 1
	v_permlane16_swap_b32_e32 v128, v129
	v_add_f32_e32 v128, v128, v129
	v_mov_b32_e32 v129, v128
	s_nop 1
	v_permlane32_swap_b32_e32 v128, v129
	s_and_saveexec_b64 s[0:1], s[38:39]
	s_cbranch_execz .LBB0_340
	s_waitcnt lgkmcnt(0)
	v_add_f32_e32 v128, v128, v129
	ds_write_b32 v244, v128 offset:1024
.LBB0_340:
	s_or_b64 exec, exec, s[0:1]
	s_waitcnt lgkmcnt(0)
	v_pk_mul_f32 v[128:129], v[110:111], v[110:111]
	v_pk_mul_f32 v[130:131], v[108:109], v[108:109]
	v_pk_fma_f32 v[128:129], v[106:107], v[106:107], v[128:129]
	v_pk_fma_f32 v[130:131], v[104:105], v[104:105], v[130:131]
	v_pk_fma_f32 v[128:129], v[102:103], v[102:103], v[128:129]
	v_pk_fma_f32 v[130:131], v[100:101], v[100:101], v[130:131]
	v_pk_fma_f32 v[128:129], v[98:99], v[98:99], v[128:129]
	v_pk_fma_f32 v[130:131], v[96:97], v[96:97], v[130:131]
	v_add_f32_e32 v128, v128, v129
	v_add_f32_e32 v130, v130, v131
	v_add_f32_e32 v128, v130, v128
	v_mov_b32_e32 v129, v128
	s_nop 1
	v_permlane16_swap_b32_e32 v128, v129
	v_add_f32_e32 v128, v128, v129
	v_mov_b32_e32 v129, v128
	s_nop 1
	v_permlane32_swap_b32_e32 v128, v129
	s_and_saveexec_b64 s[0:1], s[38:39]
	s_cbranch_execz .LBB0_342
	s_waitcnt lgkmcnt(0)
	v_add_f32_e32 v128, v128, v129
	ds_write_b32 v244, v128 offset:1280
.LBB0_342:
	s_or_b64 exec, exec, s[0:1]
	s_waitcnt lgkmcnt(0)
	v_pk_mul_f32 v[128:129], v[94:95], v[94:95]
	v_pk_mul_f32 v[130:131], v[92:93], v[92:93]
	v_pk_fma_f32 v[128:129], v[90:91], v[90:91], v[128:129]
	v_pk_fma_f32 v[130:131], v[88:89], v[88:89], v[130:131]
	v_pk_fma_f32 v[128:129], v[86:87], v[86:87], v[128:129]
	v_pk_fma_f32 v[130:131], v[84:85], v[84:85], v[130:131]
	v_pk_fma_f32 v[128:129], v[82:83], v[82:83], v[128:129]
	v_pk_fma_f32 v[130:131], v[80:81], v[80:81], v[130:131]
	v_add_f32_e32 v128, v128, v129
	v_add_f32_e32 v130, v130, v131
	v_add_f32_e32 v128, v130, v128
	v_mov_b32_e32 v129, v128
	s_nop 1
	v_permlane16_swap_b32_e32 v128, v129
	v_add_f32_e32 v128, v128, v129
	v_mov_b32_e32 v129, v128
	s_nop 1
	v_permlane32_swap_b32_e32 v128, v129
	s_and_saveexec_b64 s[0:1], s[38:39]
	s_cbranch_execz .LBB0_344
	s_waitcnt lgkmcnt(0)
	v_add_f32_e32 v128, v128, v129
	ds_write_b32 v244, v128 offset:1536
.LBB0_344:
	s_or_b64 exec, exec, s[0:1]
	s_waitcnt lgkmcnt(0)
	v_pk_mul_f32 v[128:129], v[78:79], v[78:79]
	v_pk_mul_f32 v[130:131], v[76:77], v[76:77]
	v_pk_fma_f32 v[128:129], v[74:75], v[74:75], v[128:129]
	v_pk_fma_f32 v[130:131], v[72:73], v[72:73], v[130:131]
	v_pk_fma_f32 v[128:129], v[70:71], v[70:71], v[128:129]
	v_pk_fma_f32 v[130:131], v[68:69], v[68:69], v[130:131]
	v_pk_fma_f32 v[128:129], v[66:67], v[66:67], v[128:129]
	v_pk_fma_f32 v[130:131], v[64:65], v[64:65], v[130:131]
	v_add_f32_e32 v128, v128, v129
	v_add_f32_e32 v130, v130, v131
	v_add_f32_e32 v128, v130, v128
	v_mov_b32_e32 v129, v128
	s_nop 1
	v_permlane16_swap_b32_e32 v128, v129
	v_add_f32_e32 v128, v128, v129
	v_mov_b32_e32 v129, v128
	s_nop 1
	v_permlane32_swap_b32_e32 v128, v129
	s_and_saveexec_b64 s[0:1], s[38:39]
	s_cbranch_execz .LBB0_346
	s_waitcnt lgkmcnt(0)
	v_add_f32_e32 v128, v128, v129
	ds_write_b32 v244, v128 offset:1792
.LBB0_346:
	s_or_b64 exec, exec, s[0:1]
	s_waitcnt lgkmcnt(0)
	v_pk_mul_f32 v[128:129], v[62:63], v[62:63]
	v_pk_mul_f32 v[130:131], v[60:61], v[60:61]
	v_pk_fma_f32 v[128:129], v[58:59], v[58:59], v[128:129]
	v_pk_fma_f32 v[130:131], v[56:57], v[56:57], v[130:131]
	v_pk_fma_f32 v[128:129], v[54:55], v[54:55], v[128:129]
	v_pk_fma_f32 v[130:131], v[52:53], v[52:53], v[130:131]
	v_pk_fma_f32 v[128:129], v[50:51], v[50:51], v[128:129]
	v_pk_fma_f32 v[130:131], v[48:49], v[48:49], v[130:131]
	v_add_f32_e32 v128, v128, v129
	v_add_f32_e32 v130, v130, v131
	v_add_f32_e32 v128, v130, v128
	v_mov_b32_e32 v129, v128
	s_nop 1
	v_permlane16_swap_b32_e32 v128, v129
	v_add_f32_e32 v128, v128, v129
	v_mov_b32_e32 v129, v128
	s_nop 1
	v_permlane32_swap_b32_e32 v128, v129
	s_and_saveexec_b64 s[0:1], s[38:39]
	s_cbranch_execz .LBB0_348
	s_waitcnt lgkmcnt(0)
	v_add_f32_e32 v128, v128, v129
	ds_write_b32 v244, v128 offset:3072
.LBB0_348:
	s_or_b64 exec, exec, s[0:1]
	s_waitcnt lgkmcnt(0)
	v_pk_mul_f32 v[128:129], v[46:47], v[46:47]
	v_pk_mul_f32 v[130:131], v[44:45], v[44:45]
	v_pk_fma_f32 v[128:129], v[42:43], v[42:43], v[128:129]
	v_pk_fma_f32 v[130:131], v[40:41], v[40:41], v[130:131]
	v_pk_fma_f32 v[128:129], v[38:39], v[38:39], v[128:129]
	v_pk_fma_f32 v[130:131], v[36:37], v[36:37], v[130:131]
	v_pk_fma_f32 v[128:129], v[34:35], v[34:35], v[128:129]
	v_pk_fma_f32 v[130:131], v[32:33], v[32:33], v[130:131]
	v_add_f32_e32 v128, v128, v129
	v_add_f32_e32 v130, v130, v131
	v_add_f32_e32 v128, v130, v128
	v_mov_b32_e32 v129, v128
	s_nop 1
	v_permlane16_swap_b32_e32 v128, v129
	v_add_f32_e32 v128, v128, v129
	v_mov_b32_e32 v129, v128
	s_nop 1
	v_permlane32_swap_b32_e32 v128, v129
	s_and_saveexec_b64 s[0:1], s[38:39]
	s_cbranch_execz .LBB0_350
	s_waitcnt lgkmcnt(0)
	v_add_f32_e32 v128, v128, v129
	ds_write_b32 v244, v128 offset:3328
.LBB0_350:
	s_or_b64 exec, exec, s[0:1]
	s_waitcnt lgkmcnt(0)
	v_pk_mul_f32 v[128:129], v[30:31], v[30:31]
	v_pk_mul_f32 v[130:131], v[28:29], v[28:29]
	v_pk_fma_f32 v[128:129], v[26:27], v[26:27], v[128:129]
	v_pk_fma_f32 v[130:131], v[24:25], v[24:25], v[130:131]
	v_pk_fma_f32 v[128:129], v[22:23], v[22:23], v[128:129]
	v_pk_fma_f32 v[130:131], v[20:21], v[20:21], v[130:131]
	v_pk_fma_f32 v[128:129], v[18:19], v[18:19], v[128:129]
	v_pk_fma_f32 v[130:131], v[16:17], v[16:17], v[130:131]
	v_add_f32_e32 v128, v128, v129
	v_add_f32_e32 v130, v130, v131
	v_add_f32_e32 v128, v130, v128
	v_mov_b32_e32 v129, v128
	s_nop 1
	v_permlane16_swap_b32_e32 v128, v129
	v_add_f32_e32 v128, v128, v129
	v_mov_b32_e32 v129, v128
	s_nop 1
	v_permlane32_swap_b32_e32 v128, v129
	s_and_saveexec_b64 s[0:1], s[38:39]
	s_cbranch_execz .LBB0_352
	s_waitcnt lgkmcnt(0)
	v_add_f32_e32 v128, v128, v129
	ds_write_b32 v244, v128 offset:3584
.LBB0_352:
	s_or_b64 exec, exec, s[0:1]
	s_waitcnt lgkmcnt(0)
	v_pk_mul_f32 v[128:129], v[14:15], v[14:15]
	v_pk_mul_f32 v[130:131], v[12:13], v[12:13]
	v_pk_fma_f32 v[128:129], v[10:11], v[10:11], v[128:129]
	v_pk_fma_f32 v[130:131], v[8:9], v[8:9], v[130:131]
	v_pk_fma_f32 v[128:129], v[6:7], v[6:7], v[128:129]
	v_pk_fma_f32 v[130:131], v[4:5], v[4:5], v[130:131]
	v_pk_fma_f32 v[128:129], v[2:3], v[2:3], v[128:129]
	v_pk_fma_f32 v[130:131], v[0:1], v[0:1], v[130:131]
	v_add_f32_e32 v128, v128, v129
	v_add_f32_e32 v130, v130, v131
	v_add_f32_e32 v128, v130, v128
	v_mov_b32_e32 v129, v128
	s_nop 1
	v_permlane16_swap_b32_e32 v128, v129
	v_add_f32_e32 v128, v128, v129
	v_mov_b32_e32 v129, v128
	s_nop 1
	v_permlane32_swap_b32_e32 v128, v129
	s_and_saveexec_b64 s[0:1], s[38:39]
	s_cbranch_execz .LBB0_354
	s_waitcnt lgkmcnt(0)
	v_add_f32_e32 v128, v128, v129
	ds_write_b32 v244, v128 offset:3840

.LBB0_361:
	s_or_b64 exec, exec, s[0:1]
	v_lshl_or_b32 v166, s10, 8, v156
	v_ashrrev_i32_e32 v167, 31, v166
	s_waitcnt lgkmcnt(0)
	s_barrier
	v_lshl_add_u64 v[136:137], v[166:167], 2, s[72:73]
	v_readlane_b32 s0, v255, 46
	v_readlane_b32 s1, v255, 47
	s_waitcnt vmcnt(0)
	v_pk_mul_f32 v[142:143], s[80:81], v[186:187]
	v_pk_mul_f32 v[140:141], s[0:1], v[188:189]
	v_pk_mul_f32 v[132:133], s[0:1], v[192:193]
	v_pk_mul_f32 v[134:135], s[80:81], v[190:191]
	ds_read_b32 v144, v241
	s_waitcnt lgkmcnt(0)
	v_pk_mul_f32 v[126:127], v[126:127], v[144:145] op_sel_hi:[1, 0]
	v_pk_mul_f32 v[122:123], v[122:123], v[144:145] op_sel_hi:[1, 0]
	v_pk_mul_f32 v[120:121], v[120:121], v[144:145] op_sel_hi:[1, 0]
	v_pk_mul_f32 v[124:125], v[124:125], v[144:145] op_sel_hi:[1, 0]
	v_pk_mul_f32 v[118:119], v[118:119], v[144:145] op_sel_hi:[1, 0]
	v_pk_mul_f32 v[116:117], v[116:117], v[144:145] op_sel_hi:[1, 0]
	v_pk_mul_f32 v[114:115], v[114:115], v[144:145] op_sel_hi:[1, 0]
	v_pk_mul_f32 v[112:113], v[112:113], v[144:145] op_sel_hi:[1, 0]
	v_pk_mul_f32 v[130:131], s[0:1], v[200:201]
	v_pk_mul_f32 v[138:139], s[80:81], v[194:195]
	v_add_u32_e32 v168, s24, v147
	v_ashrrev_i32_e32 v169, 31, v168
	v_pk_mul_f32 v[136:137], s[0:1], v[196:197]
	v_lshlrev_b64 v[170:171], 11, v[168:169]
	v_lshl_add_u64 v[170:171], s[4:5], 0, v[170:171]
	v_lshl_add_u64 v[170:171], v[166:167], 1, v[170:171]
	v_pk_mul_f32 v[128:129], s[80:81], v[198:199]
	v_lshlrev_b32_e32 v184, 16, v202
	v_and_b32_e32 v185, 0xffff0000, v202
	v_lshlrev_b32_e32 v176, 16, v203
	v_and_b32_e32 v177, 0xffff0000, v203
	v_pk_fma_f32 v[126:127], v[140:141], v[126:127], v[176:177]
	v_lshlrev_b32_e32 v176, 16, v204
	v_and_b32_e32 v177, 0xffff0000, v204
	v_lshlrev_b32_e32 v178, 16, v205
	v_and_b32_e32 v179, 0xffff0000, v205
	v_pk_fma_f32 v[122:123], v[132:133], v[122:123], v[178:179]
	v_pk_fma_f32 v[120:121], v[134:135], v[120:121], v[176:177]
	v_lshlrev_b32_e32 v176, 16, v206
	v_and_b32_e32 v177, 0xffff0000, v206
	v_lshlrev_b32_e32 v178, 16, v207
	v_and_b32_e32 v179, 0xffff0000, v207
	v_pk_fma_f32 v[124:125], v[142:143], v[124:125], v[184:185]
	v_pk_fma_f32 v[118:119], v[136:137], v[118:119], v[178:179]
	v_pk_fma_f32 v[116:117], v[138:139], v[116:117], v[176:177]
	v_lshlrev_b32_e32 v176, 16, v208
	v_and_b32_e32 v177, 0xffff0000, v208
	v_lshlrev_b32_e32 v178, 16, v209
	v_and_b32_e32 v179, 0xffff0000, v209
	v_pk_fma_f32 v[178:179], v[130:131], v[114:115], v[178:179]
	v_pk_fma_f32 v[176:177], v[128:129], v[112:113], v[176:177]
	s_mov_b32 s100, 0x18000
	s_mov_b32 s101, 0
	v_lshl_add_u64 v[172:173], v[218:219], 0, s[100:101]
	global_load_dwordx4 v[202:205], v[172:173], off
	global_load_dwordx4 v[206:209], v[172:173], off offset:256
	v_cvt_pk_bf16_f32 v112, v124, v125
	v_cvt_pk_bf16_f32 v113, v126, v127
	v_cvt_pk_bf16_f32 v114, v120, v121
	v_cvt_pk_bf16_f32 v115, v122, v123
	global_store_dwordx4 v[170:171], v[112:115], off
	s_nop 1
	v_cvt_pk_bf16_f32 v112, v116, v117
	v_cvt_pk_bf16_f32 v113, v118, v119
	v_cvt_pk_bf16_f32 v114, v176, v177
	v_cvt_pk_bf16_f32 v115, v178, v179
	global_store_dwordx4 v[170:171], v[112:115], off offset:256
	s_nop 1
	v_pk_mul_f32 v[112:113], v[122:123], v[122:123]
	v_pk_mul_f32 v[114:115], v[120:121], v[120:121]
	v_pk_fma_f32 v[112:113], v[126:127], v[126:127], v[112:113]
	v_pk_fma_f32 v[114:115], v[124:125], v[124:125], v[114:115]
	v_pk_fma_f32 v[112:113], v[118:119], v[118:119], v[112:113]
	v_pk_fma_f32 v[114:115], v[116:117], v[116:117], v[114:115]
	v_pk_fma_f32 v[112:113], v[178:179], v[178:179], v[112:113]
	v_pk_fma_f32 v[114:115], v[176:177], v[176:177], v[114:115]
	v_add_f32_e32 v112, v112, v113
	v_add_f32_e32 v114, v114, v115
	v_add_f32_e32 v112, v114, v112
	v_mov_b32_e32 v113, v112
	s_nop 1
	v_permlane16_swap_b32_e32 v112, v113
	v_add_f32_e32 v112, v112, v113
	v_mov_b32_e32 v113, v112
	s_nop 1
	v_permlane32_swap_b32_e32 v112, v113
	s_and_saveexec_b64 s[0:1], s[38:39]
	s_cbranch_execz .LBB0_363
	s_waitcnt lgkmcnt(0)
	v_add_f32_e32 v114, v112, v113
	s_lshl_b32 s2, s10, 2
	v_lshlrev_b64 v[112:113], 6, v[168:169]
	s_ashr_i32 s3, s2, 31
	v_lshl_add_u64 v[112:113], s[88:89], 0, v[112:113]
	v_lshl_add_u64 v[112:113], s[2:3], 2, v[112:113]
	s_lshl_b32 s24, s17, 2
	v_lshl_add_u64 v[112:113], v[112:113], 0, s[24:25]
	global_store_dword v[112:113], v114, off
.LBB0_363:
	s_or_b64 exec, exec, s[0:1]
	v_or_b32_e32 v112, 16, v168
	s_waitcnt lgkmcnt(0)
	v_ashrrev_i32_e32 v113, 31, v112
	v_lshlrev_b64 v[114:115], 11, v[112:113]
	v_lshl_add_u64 v[114:115], s[4:5], 0, v[114:115]
	v_lshl_add_u64 v[124:125], v[166:167], 1, v[114:115]
	ds_read_b32 v122, v241 offset:64
	s_waitcnt lgkmcnt(0)
	v_pk_mul_f32 v[110:111], v[110:111], v[122:123] op_sel_hi:[1, 0]
	v_pk_mul_f32 v[108:109], v[108:109], v[122:123] op_sel_hi:[1, 0]
	v_pk_mul_f32 v[106:107], v[106:107], v[122:123] op_sel_hi:[1, 0]
	v_pk_mul_f32 v[104:105], v[104:105], v[122:123] op_sel_hi:[1, 0]
	v_pk_mul_f32 v[102:103], v[102:103], v[122:123] op_sel_hi:[1, 0]
	v_pk_mul_f32 v[100:101], v[100:101], v[122:123] op_sel_hi:[1, 0]
	v_pk_mul_f32 v[98:99], v[98:99], v[122:123] op_sel_hi:[1, 0]
	v_pk_mul_f32 v[96:97], v[96:97], v[122:123] op_sel_hi:[1, 0]
	v_lshlrev_b32_e32 v122, 16, v210
	v_and_b32_e32 v123, 0xffff0000, v210
	v_lshlrev_b32_e32 v114, 16, v211
	v_and_b32_e32 v115, 0xffff0000, v211
	v_pk_fma_f32 v[110:111], v[140:141], v[110:111], v[114:115]
	v_lshlrev_b32_e32 v114, 16, v212
	v_and_b32_e32 v115, 0xffff0000, v212
	v_lshlrev_b32_e32 v116, 16, v213
	v_and_b32_e32 v117, 0xffff0000, v213
	v_pk_fma_f32 v[106:107], v[132:133], v[106:107], v[116:117]
	v_pk_fma_f32 v[104:105], v[134:135], v[104:105], v[114:115]
	v_lshlrev_b32_e32 v114, 16, v214
	v_and_b32_e32 v115, 0xffff0000, v214
	v_lshlrev_b32_e32 v116, 16, v215
	v_and_b32_e32 v117, 0xffff0000, v215
	v_pk_fma_f32 v[108:109], v[142:143], v[108:109], v[122:123]
	v_pk_fma_f32 v[102:103], v[136:137], v[102:103], v[116:117]
	v_pk_fma_f32 v[100:101], v[138:139], v[100:101], v[114:115]
	v_lshlrev_b32_e32 v114, 16, v216
	v_and_b32_e32 v115, 0xffff0000, v216
	v_lshlrev_b32_e32 v116, 16, v217
	v_and_b32_e32 v117, 0xffff0000, v217
	v_pk_fma_f32 v[116:117], v[130:131], v[98:99], v[116:117]
	v_pk_fma_f32 v[114:115], v[128:129], v[96:97], v[114:115]
	s_mov_b32 s100, 0x40000
	s_mov_b32 s101, 0
	v_lshl_add_u64 v[172:173], v[218:219], 0, s[100:101]
	global_load_dwordx4 v[210:213], v[172:173], off
	global_load_dwordx4 v[214:217], v[172:173], off offset:256
	v_cvt_pk_bf16_f32 v96, v108, v109
	v_cvt_pk_bf16_f32 v97, v110, v111
	v_cvt_pk_bf16_f32 v98, v104, v105
	v_cvt_pk_bf16_f32 v99, v106, v107
	global_store_dwordx4 v[124:125], v[96:99], off
	s_nop 1
	v_cvt_pk_bf16_f32 v96, v100, v101
	v_cvt_pk_bf16_f32 v97, v102, v103
	v_cvt_pk_bf16_f32 v98, v114, v115
	v_cvt_pk_bf16_f32 v99, v116, v117
	global_store_dwordx4 v[124:125], v[96:99], off offset:256
	s_nop 1
	v_pk_mul_f32 v[96:97], v[104:105], v[104:105]
	v_pk_mul_f32 v[98:99], v[106:107], v[106:107]
	v_pk_fma_f32 v[96:97], v[108:109], v[108:109], v[96:97]
	v_pk_fma_f32 v[98:99], v[110:111], v[110:111], v[98:99]
	v_pk_fma_f32 v[96:97], v[100:101], v[100:101], v[96:97]
	v_pk_fma_f32 v[98:99], v[102:103], v[102:103], v[98:99]
	v_pk_fma_f32 v[96:97], v[114:115], v[114:115], v[96:97]
	v_pk_fma_f32 v[98:99], v[116:117], v[116:117], v[98:99]
	v_add_f32_e32 v96, v96, v97
	v_add_f32_e32 v97, v98, v99
	v_add_f32_e32 v96, v96, v97
	v_mov_b32_e32 v97, v96
	s_nop 1
	v_permlane16_swap_b32_e32 v96, v97
	v_add_f32_e32 v96, v96, v97
	v_mov_b32_e32 v97, v96
	s_nop 1
	v_permlane32_swap_b32_e32 v96, v97
	s_and_saveexec_b64 s[0:1], s[38:39]
	s_cbranch_execz .LBB0_365
	s_waitcnt lgkmcnt(0)
	v_add_f32_e32 v98, v96, v97
	s_lshl_b32 s2, s10, 2
	v_lshlrev_b64 v[96:97], 6, v[112:113]
	s_ashr_i32 s3, s2, 31
	v_lshl_add_u64 v[96:97], s[88:89], 0, v[96:97]
	v_lshl_add_u64 v[96:97], s[2:3], 2, v[96:97]
	s_lshl_b32 s24, s17, 2
	v_lshl_add_u64 v[96:97], v[96:97], 0, s[24:25]
	global_store_dword v[96:97], v98, off
.LBB0_365:
	s_or_b64 exec, exec, s[0:1]
	v_or_b32_e32 v96, 32, v168
	s_waitcnt lgkmcnt(0)
	v_ashrrev_i32_e32 v97, 31, v96
	v_lshlrev_b64 v[98:99], 11, v[96:97]
	v_lshl_add_u64 v[98:99], s[4:5], 0, v[98:99]
	v_lshl_add_u64 v[108:109], v[166:167], 1, v[98:99]
	ds_read_b32 v106, v241 offset:128
	s_waitcnt lgkmcnt(0)
	v_pk_mul_f32 v[94:95], v[94:95], v[106:107] op_sel_hi:[1, 0]
	v_pk_mul_f32 v[92:93], v[92:93], v[106:107] op_sel_hi:[1, 0]
	v_pk_mul_f32 v[90:91], v[90:91], v[106:107] op_sel_hi:[1, 0]
	v_pk_mul_f32 v[88:89], v[88:89], v[106:107] op_sel_hi:[1, 0]
	v_pk_mul_f32 v[86:87], v[86:87], v[106:107] op_sel_hi:[1, 0]
	v_pk_mul_f32 v[84:85], v[84:85], v[106:107] op_sel_hi:[1, 0]
	v_pk_mul_f32 v[82:83], v[82:83], v[106:107] op_sel_hi:[1, 0]
	v_pk_mul_f32 v[80:81], v[80:81], v[106:107] op_sel_hi:[1, 0]
	v_lshlrev_b32_e32 v106, 16, v232
	v_and_b32_e32 v107, 0xffff0000, v232
	v_lshlrev_b32_e32 v98, 16, v233
	v_and_b32_e32 v99, 0xffff0000, v233
	v_pk_fma_f32 v[94:95], v[140:141], v[94:95], v[98:99]
	v_lshlrev_b32_e32 v98, 16, v234
	v_and_b32_e32 v99, 0xffff0000, v234
	v_lshlrev_b32_e32 v100, 16, v235
	v_and_b32_e32 v101, 0xffff0000, v235
	v_pk_fma_f32 v[90:91], v[132:133], v[90:91], v[100:101]
	v_pk_fma_f32 v[88:89], v[134:135], v[88:89], v[98:99]
	v_lshlrev_b32_e32 v98, 16, v246
	v_and_b32_e32 v99, 0xffff0000, v246
	v_lshlrev_b32_e32 v100, 16, v247
	v_and_b32_e32 v101, 0xffff0000, v247
	v_pk_fma_f32 v[92:93], v[142:143], v[92:93], v[106:107]
	v_pk_fma_f32 v[86:87], v[136:137], v[86:87], v[100:101]
	v_pk_fma_f32 v[84:85], v[138:139], v[84:85], v[98:99]
	v_lshlrev_b32_e32 v98, 16, v248
	v_and_b32_e32 v99, 0xffff0000, v248
	v_lshlrev_b32_e32 v100, 16, v249
	v_and_b32_e32 v101, 0xffff0000, v249
	v_pk_fma_f32 v[100:101], v[130:131], v[82:83], v[100:101]
	v_pk_fma_f32 v[98:99], v[128:129], v[80:81], v[98:99]
	s_mov_b32 s100, 0x48000
	s_mov_b32 s101, 0
	v_lshl_add_u64 v[172:173], v[218:219], 0, s[100:101]
	global_load_dwordx4 v[232:235], v[172:173], off
	global_load_dwordx4 v[246:249], v[172:173], off offset:256
	v_cvt_pk_bf16_f32 v80, v92, v93
	v_cvt_pk_bf16_f32 v81, v94, v95
	v_cvt_pk_bf16_f32 v82, v88, v89
	v_cvt_pk_bf16_f32 v83, v90, v91
	global_store_dwordx4 v[108:109], v[80:83], off
	s_nop 1
	v_cvt_pk_bf16_f32 v80, v84, v85
	v_cvt_pk_bf16_f32 v81, v86, v87
	v_cvt_pk_bf16_f32 v82, v98, v99
	v_cvt_pk_bf16_f32 v83, v100, v101
	global_store_dwordx4 v[108:109], v[80:83], off offset:256
	s_nop 1
	v_pk_mul_f32 v[80:81], v[88:89], v[88:89]
	v_pk_mul_f32 v[82:83], v[90:91], v[90:91]
	v_pk_fma_f32 v[80:81], v[92:93], v[92:93], v[80:81]
	v_pk_fma_f32 v[82:83], v[94:95], v[94:95], v[82:83]
	v_pk_fma_f32 v[80:81], v[84:85], v[84:85], v[80:81]
	v_pk_fma_f32 v[82:83], v[86:87], v[86:87], v[82:83]
	v_pk_fma_f32 v[80:81], v[98:99], v[98:99], v[80:81]
	v_pk_fma_f32 v[82:83], v[100:101], v[100:101], v[82:83]
	v_add_f32_e32 v80, v80, v81
	v_add_f32_e32 v81, v82, v83
	v_add_f32_e32 v80, v80, v81
	v_mov_b32_e32 v81, v80
	s_nop 1
	v_permlane16_swap_b32_e32 v80, v81
	v_add_f32_e32 v80, v80, v81
	v_mov_b32_e32 v81, v80
	s_nop 1
	v_permlane32_swap_b32_e32 v80, v81
	s_and_saveexec_b64 s[0:1], s[38:39]
	s_cbranch_execz .LBB0_367
	s_waitcnt lgkmcnt(0)
	v_add_f32_e32 v82, v80, v81
	s_lshl_b32 s2, s10, 2
	v_lshlrev_b64 v[80:81], 6, v[96:97]
	s_ashr_i32 s3, s2, 31
	v_lshl_add_u64 v[80:81], s[88:89], 0, v[80:81]
	v_lshl_add_u64 v[80:81], s[2:3], 2, v[80:81]
	s_lshl_b32 s24, s17, 2
	v_lshl_add_u64 v[80:81], v[80:81], 0, s[24:25]
	global_store_dword v[80:81], v82, off
.LBB0_367:
	s_or_b64 exec, exec, s[0:1]
	v_or_b32_e32 v80, 48, v168
	s_waitcnt lgkmcnt(0)
	v_ashrrev_i32_e32 v81, 31, v80
	v_lshlrev_b64 v[82:83], 11, v[80:81]
	v_lshl_add_u64 v[82:83], s[4:5], 0, v[82:83]
	v_lshl_add_u64 v[92:93], v[166:167], 1, v[82:83]
	ds_read_b32 v90, v241 offset:192
	s_waitcnt lgkmcnt(0)
	v_pk_mul_f32 v[78:79], v[78:79], v[90:91] op_sel_hi:[1, 0]
	v_pk_mul_f32 v[76:77], v[76:77], v[90:91] op_sel_hi:[1, 0]
	v_pk_mul_f32 v[74:75], v[74:75], v[90:91] op_sel_hi:[1, 0]
	v_pk_mul_f32 v[72:73], v[72:73], v[90:91] op_sel_hi:[1, 0]
	v_pk_mul_f32 v[70:71], v[70:71], v[90:91] op_sel_hi:[1, 0]
	v_pk_mul_f32 v[68:69], v[68:69], v[90:91] op_sel_hi:[1, 0]
	v_pk_mul_f32 v[66:67], v[66:67], v[90:91] op_sel_hi:[1, 0]
	v_pk_mul_f32 v[64:65], v[64:65], v[90:91] op_sel_hi:[1, 0]
	s_waitcnt vmcnt(10)
	v_lshlrev_b32_e32 v90, 16, v202
	v_and_b32_e32 v91, 0xffff0000, v202
	v_lshlrev_b32_e32 v82, 16, v203
	v_and_b32_e32 v83, 0xffff0000, v203
	v_pk_fma_f32 v[78:79], v[140:141], v[78:79], v[82:83]
	v_lshlrev_b32_e32 v82, 16, v204
	v_and_b32_e32 v83, 0xffff0000, v204
	v_lshlrev_b32_e32 v84, 16, v205
	v_and_b32_e32 v85, 0xffff0000, v205
	v_pk_fma_f32 v[74:75], v[132:133], v[74:75], v[84:85]
	v_pk_fma_f32 v[72:73], v[134:135], v[72:73], v[82:83]
	v_lshlrev_b32_e32 v82, 16, v206
	v_and_b32_e32 v83, 0xffff0000, v206
	v_lshlrev_b32_e32 v84, 16, v207
	v_and_b32_e32 v85, 0xffff0000, v207
	v_pk_fma_f32 v[76:77], v[142:143], v[76:77], v[90:91]
	v_pk_fma_f32 v[70:71], v[136:137], v[70:71], v[84:85]
	v_pk_fma_f32 v[68:69], v[138:139], v[68:69], v[82:83]
	v_lshlrev_b32_e32 v82, 16, v208
	v_and_b32_e32 v83, 0xffff0000, v208
	v_lshlrev_b32_e32 v84, 16, v209
	v_and_b32_e32 v85, 0xffff0000, v209
	v_pk_fma_f32 v[84:85], v[130:131], v[66:67], v[84:85]
	v_pk_fma_f32 v[82:83], v[128:129], v[64:65], v[82:83]
	s_mov_b32 s100, 0x50000
	s_mov_b32 s101, 0
	v_lshl_add_u64 v[172:173], v[218:219], 0, s[100:101]
	global_load_dwordx4 v[202:205], v[172:173], off
	global_load_dwordx4 v[206:209], v[172:173], off offset:256
	v_cvt_pk_bf16_f32 v64, v76, v77
	v_cvt_pk_bf16_f32 v65, v78, v79
	v_cvt_pk_bf16_f32 v66, v72, v73
	v_cvt_pk_bf16_f32 v67, v74, v75
	global_store_dwordx4 v[92:93], v[64:67], off
	s_nop 1
	v_cvt_pk_bf16_f32 v64, v68, v69
	v_cvt_pk_bf16_f32 v65, v70, v71
	v_cvt_pk_bf16_f32 v66, v82, v83
	v_cvt_pk_bf16_f32 v67, v84, v85
	global_store_dwordx4 v[92:93], v[64:67], off offset:256
	s_nop 1
	v_pk_mul_f32 v[64:65], v[72:73], v[72:73]
	v_pk_mul_f32 v[66:67], v[74:75], v[74:75]
	v_pk_fma_f32 v[64:65], v[76:77], v[76:77], v[64:65]
	v_pk_fma_f32 v[66:67], v[78:79], v[78:79], v[66:67]
	v_pk_fma_f32 v[64:65], v[68:69], v[68:69], v[64:65]
	v_pk_fma_f32 v[66:67], v[70:71], v[70:71], v[66:67]
	v_pk_fma_f32 v[64:65], v[82:83], v[82:83], v[64:65]
	v_pk_fma_f32 v[66:67], v[84:85], v[84:85], v[66:67]
	v_add_f32_e32 v64, v64, v65
	v_add_f32_e32 v65, v66, v67
	v_add_f32_e32 v64, v64, v65
	v_mov_b32_e32 v65, v64
	s_nop 1
	v_permlane16_swap_b32_e32 v64, v65
	v_add_f32_e32 v64, v64, v65
	v_mov_b32_e32 v65, v64
	s_nop 1
	v_permlane32_swap_b32_e32 v64, v65
	s_and_saveexec_b64 s[0:1], s[38:39]
	s_cbranch_execz .LBB0_369
	s_waitcnt lgkmcnt(0)
	v_add_f32_e32 v66, v64, v65
	s_lshl_b32 s2, s10, 2
	v_lshlrev_b64 v[64:65], 6, v[80:81]
	s_ashr_i32 s3, s2, 31
	v_lshl_add_u64 v[64:65], s[88:89], 0, v[64:65]
	v_lshl_add_u64 v[64:65], s[2:3], 2, v[64:65]
	s_lshl_b32 s24, s17, 2
	v_lshl_add_u64 v[64:65], v[64:65], 0, s[24:25]
	global_store_dword v[64:65], v66, off
.LBB0_369:
	s_or_b64 exec, exec, s[0:1]
	v_add_u32_e32 v64, 0x80, v168
	s_waitcnt lgkmcnt(0)
	v_ashrrev_i32_e32 v65, 31, v64
	v_lshlrev_b64 v[66:67], 11, v[64:65]
	v_lshl_add_u64 v[66:67], s[4:5], 0, v[66:67]
	v_lshl_add_u64 v[76:77], v[166:167], 1, v[66:67]
	ds_read_b32 v74, v241 offset:512
	s_waitcnt lgkmcnt(0)
	v_pk_mul_f32 v[62:63], v[62:63], v[74:75] op_sel_hi:[1, 0]
	v_pk_mul_f32 v[60:61], v[60:61], v[74:75] op_sel_hi:[1, 0]
	v_pk_mul_f32 v[58:59], v[58:59], v[74:75] op_sel_hi:[1, 0]
	v_pk_mul_f32 v[56:57], v[56:57], v[74:75] op_sel_hi:[1, 0]
	v_pk_mul_f32 v[54:55], v[54:55], v[74:75] op_sel_hi:[1, 0]
	v_pk_mul_f32 v[52:53], v[52:53], v[74:75] op_sel_hi:[1, 0]
	v_pk_mul_f32 v[50:51], v[50:51], v[74:75] op_sel_hi:[1, 0]
	v_pk_mul_f32 v[48:49], v[48:49], v[74:75] op_sel_hi:[1, 0]
	s_waitcnt vmcnt(10)
	v_lshlrev_b32_e32 v74, 16, v210
	v_and_b32_e32 v75, 0xffff0000, v210
	v_lshlrev_b32_e32 v66, 16, v211
	v_and_b32_e32 v67, 0xffff0000, v211
	v_pk_fma_f32 v[62:63], v[140:141], v[62:63], v[66:67]
	v_lshlrev_b32_e32 v66, 16, v212
	v_and_b32_e32 v67, 0xffff0000, v212
	v_lshlrev_b32_e32 v68, 16, v213
	v_and_b32_e32 v69, 0xffff0000, v213
	v_pk_fma_f32 v[58:59], v[132:133], v[58:59], v[68:69]
	v_pk_fma_f32 v[56:57], v[134:135], v[56:57], v[66:67]
	v_lshlrev_b32_e32 v66, 16, v214
	v_and_b32_e32 v67, 0xffff0000, v214
	v_lshlrev_b32_e32 v68, 16, v215
	v_and_b32_e32 v69, 0xffff0000, v215
	v_pk_fma_f32 v[60:61], v[142:143], v[60:61], v[74:75]
	v_pk_fma_f32 v[54:55], v[136:137], v[54:55], v[68:69]
	v_pk_fma_f32 v[52:53], v[138:139], v[52:53], v[66:67]
	v_lshlrev_b32_e32 v66, 16, v216
	v_and_b32_e32 v67, 0xffff0000, v216
	v_lshlrev_b32_e32 v68, 16, v217
	v_and_b32_e32 v69, 0xffff0000, v217
	v_pk_fma_f32 v[68:69], v[130:131], v[50:51], v[68:69]
	v_pk_fma_f32 v[66:67], v[128:129], v[48:49], v[66:67]
	s_mov_b32 s100, 0x58000
	s_mov_b32 s101, 0
	v_lshl_add_u64 v[172:173], v[218:219], 0, s[100:101]
	global_load_dwordx4 v[210:213], v[172:173], off
	global_load_dwordx4 v[214:217], v[172:173], off offset:256
	v_cvt_pk_bf16_f32 v48, v60, v61
	v_cvt_pk_bf16_f32 v49, v62, v63
	v_cvt_pk_bf16_f32 v50, v56, v57
	v_cvt_pk_bf16_f32 v51, v58, v59
	global_store_dwordx4 v[76:77], v[48:51], off
	s_nop 1
	v_cvt_pk_bf16_f32 v48, v52, v53
	v_cvt_pk_bf16_f32 v49, v54, v55
	v_cvt_pk_bf16_f32 v50, v66, v67
	v_cvt_pk_bf16_f32 v51, v68, v69
	global_store_dwordx4 v[76:77], v[48:51], off offset:256
	s_nop 1
	v_pk_mul_f32 v[48:49], v[56:57], v[56:57]
	v_pk_mul_f32 v[50:51], v[58:59], v[58:59]
	v_pk_fma_f32 v[48:49], v[60:61], v[60:61], v[48:49]
	v_pk_fma_f32 v[50:51], v[62:63], v[62:63], v[50:51]
	v_pk_fma_f32 v[48:49], v[52:53], v[52:53], v[48:49]
	v_pk_fma_f32 v[50:51], v[54:55], v[54:55], v[50:51]
	v_pk_fma_f32 v[48:49], v[66:67], v[66:67], v[48:49]
	v_pk_fma_f32 v[50:51], v[68:69], v[68:69], v[50:51]
	v_add_f32_e32 v48, v48, v49
	v_add_f32_e32 v49, v50, v51
	v_add_f32_e32 v48, v48, v49
	v_mov_b32_e32 v49, v48
	s_nop 1
	v_permlane16_swap_b32_e32 v48, v49
	v_add_f32_e32 v48, v48, v49
	v_mov_b32_e32 v49, v48
	s_nop 1
	v_permlane32_swap_b32_e32 v48, v49
	s_and_saveexec_b64 s[0:1], s[38:39]
	s_cbranch_execz .LBB0_371
	s_waitcnt lgkmcnt(0)
	v_add_f32_e32 v50, v48, v49
	s_lshl_b32 s2, s10, 2
	v_lshlrev_b64 v[48:49], 6, v[64:65]
	s_ashr_i32 s3, s2, 31
	v_lshl_add_u64 v[48:49], s[88:89], 0, v[48:49]
	v_lshl_add_u64 v[48:49], s[2:3], 2, v[48:49]
	s_lshl_b32 s24, s17, 2
	v_lshl_add_u64 v[48:49], v[48:49], 0, s[24:25]
	global_store_dword v[48:49], v50, off
.LBB0_371:
	s_or_b64 exec, exec, s[0:1]
	v_add_u32_e32 v48, 0x90, v168
	s_waitcnt lgkmcnt(0)
	v_ashrrev_i32_e32 v49, 31, v48
	v_lshlrev_b64 v[50:51], 11, v[48:49]
	v_lshl_add_u64 v[50:51], s[4:5], 0, v[50:51]
	v_lshl_add_u64 v[60:61], v[166:167], 1, v[50:51]
	ds_read_b32 v58, v241 offset:576
	s_waitcnt lgkmcnt(0)
	v_pk_mul_f32 v[46:47], v[46:47], v[58:59] op_sel_hi:[1, 0]
	v_pk_mul_f32 v[44:45], v[44:45], v[58:59] op_sel_hi:[1, 0]
	v_pk_mul_f32 v[42:43], v[42:43], v[58:59] op_sel_hi:[1, 0]
	v_pk_mul_f32 v[40:41], v[40:41], v[58:59] op_sel_hi:[1, 0]
	v_pk_mul_f32 v[38:39], v[38:39], v[58:59] op_sel_hi:[1, 0]
	v_pk_mul_f32 v[36:37], v[36:37], v[58:59] op_sel_hi:[1, 0]
	v_pk_mul_f32 v[34:35], v[34:35], v[58:59] op_sel_hi:[1, 0]
	v_pk_mul_f32 v[32:33], v[32:33], v[58:59] op_sel_hi:[1, 0]
	s_waitcnt vmcnt(10)
	v_lshlrev_b32_e32 v58, 16, v232
	v_and_b32_e32 v59, 0xffff0000, v232
	v_lshlrev_b32_e32 v50, 16, v233
	v_and_b32_e32 v51, 0xffff0000, v233
	v_pk_fma_f32 v[46:47], v[140:141], v[46:47], v[50:51]
	v_lshlrev_b32_e32 v50, 16, v234
	v_and_b32_e32 v51, 0xffff0000, v234
	v_lshlrev_b32_e32 v52, 16, v235
	v_and_b32_e32 v53, 0xffff0000, v235
	v_pk_fma_f32 v[42:43], v[132:133], v[42:43], v[52:53]
	v_pk_fma_f32 v[40:41], v[134:135], v[40:41], v[50:51]
	v_lshlrev_b32_e32 v50, 16, v246
	v_and_b32_e32 v51, 0xffff0000, v246
	v_lshlrev_b32_e32 v52, 16, v247
	v_and_b32_e32 v53, 0xffff0000, v247
	v_pk_fma_f32 v[44:45], v[142:143], v[44:45], v[58:59]
	v_pk_fma_f32 v[38:39], v[136:137], v[38:39], v[52:53]
	v_pk_fma_f32 v[36:37], v[138:139], v[36:37], v[50:51]
	v_lshlrev_b32_e32 v50, 16, v248
	v_and_b32_e32 v51, 0xffff0000, v248
	v_lshlrev_b32_e32 v52, 16, v249
	v_and_b32_e32 v53, 0xffff0000, v249
	v_pk_fma_f32 v[52:53], v[130:131], v[34:35], v[52:53]
	v_pk_fma_f32 v[50:51], v[128:129], v[32:33], v[50:51]
	v_cvt_pk_bf16_f32 v32, v44, v45
	v_cvt_pk_bf16_f32 v33, v46, v47
	v_cvt_pk_bf16_f32 v34, v40, v41
	v_cvt_pk_bf16_f32 v35, v42, v43
	global_store_dwordx4 v[60:61], v[32:35], off
	s_nop 1
	v_cvt_pk_bf16_f32 v32, v36, v37
	v_cvt_pk_bf16_f32 v33, v38, v39
	v_cvt_pk_bf16_f32 v34, v50, v51
	v_cvt_pk_bf16_f32 v35, v52, v53
	global_store_dwordx4 v[60:61], v[32:35], off offset:256
	s_nop 1
	v_pk_mul_f32 v[32:33], v[40:41], v[40:41]
	v_pk_mul_f32 v[34:35], v[42:43], v[42:43]
	v_pk_fma_f32 v[32:33], v[44:45], v[44:45], v[32:33]
	v_pk_fma_f32 v[34:35], v[46:47], v[46:47], v[34:35]
	v_pk_fma_f32 v[32:33], v[36:37], v[36:37], v[32:33]
	v_pk_fma_f32 v[34:35], v[38:39], v[38:39], v[34:35]
	v_pk_fma_f32 v[32:33], v[50:51], v[50:51], v[32:33]
	v_pk_fma_f32 v[34:35], v[52:53], v[52:53], v[34:35]
	v_add_f32_e32 v32, v32, v33
	v_add_f32_e32 v33, v34, v35
	v_add_f32_e32 v32, v32, v33
	v_mov_b32_e32 v33, v32
	s_nop 1
	v_permlane16_swap_b32_e32 v32, v33
	v_add_f32_e32 v32, v32, v33
	v_mov_b32_e32 v33, v32
	s_nop 1
	v_permlane32_swap_b32_e32 v32, v33
	s_and_saveexec_b64 s[0:1], s[38:39]
	s_cbranch_execz .LBB0_373
	s_waitcnt lgkmcnt(0)
	v_add_f32_e32 v34, v32, v33
	s_lshl_b32 s2, s10, 2
	v_lshlrev_b64 v[32:33], 6, v[48:49]
	s_ashr_i32 s3, s2, 31
	v_lshl_add_u64 v[32:33], s[88:89], 0, v[32:33]
	v_lshl_add_u64 v[32:33], s[2:3], 2, v[32:33]
	s_lshl_b32 s24, s17, 2
	v_lshl_add_u64 v[32:33], v[32:33], 0, s[24:25]
	global_store_dword v[32:33], v34, off
.LBB0_373:
	s_or_b64 exec, exec, s[0:1]
	v_add_u32_e32 v32, 0xa0, v168
	s_waitcnt lgkmcnt(0)
	v_ashrrev_i32_e32 v33, 31, v32
	v_lshlrev_b64 v[34:35], 11, v[32:33]
	v_lshl_add_u64 v[34:35], s[4:5], 0, v[34:35]
	v_lshl_add_u64 v[44:45], v[166:167], 1, v[34:35]
	ds_read_b32 v42, v241 offset:640
	s_waitcnt lgkmcnt(0)
	v_pk_mul_f32 v[30:31], v[30:31], v[42:43] op_sel_hi:[1, 0]
	v_pk_mul_f32 v[28:29], v[28:29], v[42:43] op_sel_hi:[1, 0]
	v_pk_mul_f32 v[26:27], v[26:27], v[42:43] op_sel_hi:[1, 0]
	v_pk_mul_f32 v[24:25], v[24:25], v[42:43] op_sel_hi:[1, 0]
	v_pk_mul_f32 v[22:23], v[22:23], v[42:43] op_sel_hi:[1, 0]
	v_pk_mul_f32 v[20:21], v[20:21], v[42:43] op_sel_hi:[1, 0]
	v_pk_mul_f32 v[18:19], v[18:19], v[42:43] op_sel_hi:[1, 0]
	v_pk_mul_f32 v[16:17], v[16:17], v[42:43] op_sel_hi:[1, 0]
	s_waitcnt vmcnt(8)
	v_lshlrev_b32_e32 v42, 16, v202
	v_and_b32_e32 v43, 0xffff0000, v202
	v_lshlrev_b32_e32 v34, 16, v203
	v_and_b32_e32 v35, 0xffff0000, v203
	v_pk_fma_f32 v[30:31], v[140:141], v[30:31], v[34:35]
	v_lshlrev_b32_e32 v34, 16, v204
	v_and_b32_e32 v35, 0xffff0000, v204
	v_lshlrev_b32_e32 v36, 16, v205
	v_and_b32_e32 v37, 0xffff0000, v205
	v_pk_fma_f32 v[26:27], v[132:133], v[26:27], v[36:37]
	v_pk_fma_f32 v[24:25], v[134:135], v[24:25], v[34:35]
	v_lshlrev_b32_e32 v34, 16, v206
	v_and_b32_e32 v35, 0xffff0000, v206
	v_lshlrev_b32_e32 v36, 16, v207
	v_and_b32_e32 v37, 0xffff0000, v207
	v_pk_fma_f32 v[28:29], v[142:143], v[28:29], v[42:43]
	v_pk_fma_f32 v[22:23], v[136:137], v[22:23], v[36:37]
	v_pk_fma_f32 v[20:21], v[138:139], v[20:21], v[34:35]
	v_lshlrev_b32_e32 v34, 16, v208
	v_and_b32_e32 v35, 0xffff0000, v208
	v_lshlrev_b32_e32 v36, 16, v209
	v_and_b32_e32 v37, 0xffff0000, v209
	v_pk_fma_f32 v[36:37], v[130:131], v[18:19], v[36:37]
	v_pk_fma_f32 v[34:35], v[128:129], v[16:17], v[34:35]
	v_cvt_pk_bf16_f32 v16, v28, v29
	v_cvt_pk_bf16_f32 v17, v30, v31
	v_cvt_pk_bf16_f32 v18, v24, v25
	v_cvt_pk_bf16_f32 v19, v26, v27
	global_store_dwordx4 v[44:45], v[16:19], off
	s_nop 1
	v_cvt_pk_bf16_f32 v16, v20, v21
	v_cvt_pk_bf16_f32 v17, v22, v23
	v_cvt_pk_bf16_f32 v18, v34, v35
	v_cvt_pk_bf16_f32 v19, v36, v37
	global_store_dwordx4 v[44:45], v[16:19], off offset:256
	s_nop 1
	v_pk_mul_f32 v[16:17], v[24:25], v[24:25]
	v_pk_mul_f32 v[18:19], v[26:27], v[26:27]
	v_pk_fma_f32 v[16:17], v[28:29], v[28:29], v[16:17]
	v_pk_fma_f32 v[18:19], v[30:31], v[30:31], v[18:19]
	v_pk_fma_f32 v[16:17], v[20:21], v[20:21], v[16:17]
	v_pk_fma_f32 v[18:19], v[22:23], v[22:23], v[18:19]
	v_pk_fma_f32 v[16:17], v[34:35], v[34:35], v[16:17]
	v_pk_fma_f32 v[18:19], v[36:37], v[36:37], v[18:19]
	v_add_f32_e32 v16, v16, v17
	v_add_f32_e32 v17, v18, v19
	v_add_f32_e32 v16, v16, v17
	v_mov_b32_e32 v17, v16
	s_nop 1
	v_permlane16_swap_b32_e32 v16, v17
	v_add_f32_e32 v16, v16, v17
	v_mov_b32_e32 v17, v16
	s_nop 1
	v_permlane32_swap_b32_e32 v16, v17
	s_and_saveexec_b64 s[0:1], s[38:39]
	s_cbranch_execz .LBB0_375
	s_waitcnt lgkmcnt(0)
	v_add_f32_e32 v18, v16, v17
	s_lshl_b32 s2, s10, 2
	v_lshlrev_b64 v[16:17], 6, v[32:33]
	s_ashr_i32 s3, s2, 31
	v_lshl_add_u64 v[16:17], s[88:89], 0, v[16:17]
	v_lshl_add_u64 v[16:17], s[2:3], 2, v[16:17]
	s_lshl_b32 s24, s17, 2
	v_lshl_add_u64 v[16:17], v[16:17], 0, s[24:25]
	global_store_dword v[16:17], v18, off
.LBB0_375:
	s_or_b64 exec, exec, s[0:1]
	v_add_u32_e32 v16, 0xb0, v168
	s_waitcnt lgkmcnt(0)
	v_ashrrev_i32_e32 v17, 31, v16
	v_lshlrev_b64 v[18:19], 11, v[16:17]
	v_lshl_add_u64 v[18:19], s[4:5], 0, v[18:19]
	v_lshl_add_u64 v[28:29], v[166:167], 1, v[18:19]
	ds_read_b32 v26, v241 offset:704
	s_waitcnt lgkmcnt(0)
	v_pk_mul_f32 v[14:15], v[14:15], v[26:27] op_sel_hi:[1, 0]
	v_pk_mul_f32 v[12:13], v[12:13], v[26:27] op_sel_hi:[1, 0]
	v_pk_mul_f32 v[10:11], v[10:11], v[26:27] op_sel_hi:[1, 0]
	v_pk_mul_f32 v[8:9], v[8:9], v[26:27] op_sel_hi:[1, 0]
	v_pk_mul_f32 v[6:7], v[6:7], v[26:27] op_sel_hi:[1, 0]
	v_pk_mul_f32 v[4:5], v[4:5], v[26:27] op_sel_hi:[1, 0]
	v_pk_mul_f32 v[2:3], v[2:3], v[26:27] op_sel_hi:[1, 0]
	v_pk_mul_f32 v[0:1], v[0:1], v[26:27] op_sel_hi:[1, 0]
	s_waitcnt vmcnt(6)
	v_lshlrev_b32_e32 v26, 16, v210
	v_and_b32_e32 v27, 0xffff0000, v210
	v_lshlrev_b32_e32 v18, 16, v211
	v_and_b32_e32 v19, 0xffff0000, v211
	v_pk_fma_f32 v[14:15], v[140:141], v[14:15], v[18:19]
	v_lshlrev_b32_e32 v18, 16, v212
	v_and_b32_e32 v19, 0xffff0000, v212
	v_lshlrev_b32_e32 v20, 16, v213
	v_and_b32_e32 v21, 0xffff0000, v213
	v_pk_fma_f32 v[10:11], v[132:133], v[10:11], v[20:21]
	v_pk_fma_f32 v[8:9], v[134:135], v[8:9], v[18:19]
	v_lshlrev_b32_e32 v18, 16, v214
	v_and_b32_e32 v19, 0xffff0000, v214
	v_lshlrev_b32_e32 v20, 16, v215
	v_and_b32_e32 v21, 0xffff0000, v215
	v_pk_fma_f32 v[12:13], v[142:143], v[12:13], v[26:27]
	v_pk_fma_f32 v[6:7], v[136:137], v[6:7], v[20:21]
	v_pk_fma_f32 v[4:5], v[138:139], v[4:5], v[18:19]
	v_lshlrev_b32_e32 v18, 16, v216
	v_and_b32_e32 v19, 0xffff0000, v216
	v_lshlrev_b32_e32 v20, 16, v217
	v_and_b32_e32 v21, 0xffff0000, v217
	v_pk_fma_f32 v[20:21], v[130:131], v[2:3], v[20:21]
	v_pk_fma_f32 v[18:19], v[128:129], v[0:1], v[18:19]
	v_cvt_pk_bf16_f32 v0, v12, v13
	v_cvt_pk_bf16_f32 v1, v14, v15
	v_cvt_pk_bf16_f32 v2, v8, v9
	v_cvt_pk_bf16_f32 v3, v10, v11
	global_store_dwordx4 v[28:29], v[0:3], off
	s_nop 1
	v_cvt_pk_bf16_f32 v0, v4, v5
	v_cvt_pk_bf16_f32 v1, v6, v7
	v_cvt_pk_bf16_f32 v2, v18, v19
	v_cvt_pk_bf16_f32 v3, v20, v21
	global_store_dwordx4 v[28:29], v[0:3], off offset:256
	s_nop 1
	v_pk_mul_f32 v[0:1], v[8:9], v[8:9]
	v_pk_mul_f32 v[2:3], v[10:11], v[10:11]
	v_pk_fma_f32 v[0:1], v[12:13], v[12:13], v[0:1]
	v_pk_fma_f32 v[2:3], v[14:15], v[14:15], v[2:3]
	v_pk_fma_f32 v[0:1], v[4:5], v[4:5], v[0:1]
	v_pk_fma_f32 v[2:3], v[6:7], v[6:7], v[2:3]
	v_pk_fma_f32 v[0:1], v[18:19], v[18:19], v[0:1]
	v_pk_fma_f32 v[2:3], v[20:21], v[20:21], v[2:3]
	v_add_f32_e32 v0, v0, v1
	v_add_f32_e32 v1, v2, v3
	v_add_f32_e32 v0, v0, v1
	v_mov_b32_e32 v1, v0
	s_nop 1
	v_permlane16_swap_b32_e32 v0, v1
	v_add_f32_e32 v0, v0, v1
	v_mov_b32_e32 v1, v0
	s_nop 1
	v_permlane32_swap_b32_e32 v0, v1
	s_and_saveexec_b64 s[0:1], s[38:39]
	s_cbranch_execz .LBB0_377
	s_waitcnt lgkmcnt(0)
	v_add_f32_e32 v2, v0, v1
	s_lshl_b32 s2, s10, 2
	v_lshlrev_b64 v[0:1], 6, v[16:17]
	s_ashr_i32 s3, s2, 31
	v_lshl_add_u64 v[0:1], s[88:89], 0, v[0:1]
	v_lshl_add_u64 v[0:1], s[2:3], 2, v[0:1]
	s_lshl_b32 s24, s17, 2
	v_lshl_add_u64 v[0:1], v[0:1], 0, s[24:25]
	global_store_dword v[0:1], v2, off
